# HID (FF1 out / FF2 A) stored as 64 k-slabs [T][64] instead of row-major [T][4096]: P8 epilogue + P9 A addressing
# speedup vs baseline: 1.0124x; 1.0123x over previous
.LBB0_867:
	s_lshl_b32 s12, s12, 5
	s_and_b32 s18, s12, 0x60
	s_mov_b64 s[12:13], 0x80
	s_add_i32 m0, s35, 0x18000
	v_lshl_add_u64 v[6:7], v[6:7], 0, s[12:13]
	s_ashr_i32 s46, s92, 31
	s_lshl_b32 s15, s14, 13
	s_lshl_b32 s19, s18, 7
	s_waitcnt vmcnt(2)
	s_barrier
	global_load_lds_dwordx4 v[6:7], off
	v_lshl_add_u64 v[4:5], v[4:5], 0, s[12:13]
	s_add_i32 m0, s35, 0x1a000
	s_add_i32 s47, s35, 0x8000
	s_add_i32 s48, s35, 0xa000
	global_load_lds_dwordx4 v[4:5], off
	v_lshl_add_u64 v[0:1], v[0:1], 0, s[12:13]
	s_mov_b32 m0, s47
	s_add_u32 s16, s38, 0x40080
	global_load_lds_dwordx4 v[0:1], off
	v_lshl_add_u64 v[0:1], v[2:3], 0, s[12:13]
	s_mov_b32 m0, s48
	s_addc_u32 s17, s39, 0
	global_load_lds_dwordx4 v[0:1], off
	s_add_i32 m0, s35, 0x1c000
	v_lshl_add_u64 v[0:1], s[16:17], 0, v[130:131]
	global_load_lds_dwordx4 v[0:1], off
	v_lshl_add_u64 v[0:1], s[16:17], 0, v[134:135]
	s_add_i32 m0, s35, 0x1e000
	s_sext_i32_i8 s56, s4
	global_load_lds_dwordx4 v[0:1], off
	v_and_b32_e32 v0, 15, v220
	v_lshlrev_b32_e32 v1, 1, v11
	v_lshlrev_b32_e32 v2, 6, v220
	s_movk_i32 s4, 0x3c0
	v_lshlrev_b32_e32 v3, 2, v220
	v_and_or_b32 v2, v2, s4, v1
	v_and_b32_e32 v3, 32, v3
	v_lshl_or_b32 v144, s14, 6, v0
	v_lshl_or_b32 v0, v0, 6, v1
	v_lshlrev_b32_e32 v1, 8, v220
	v_bitop3_b32 v145, s19, v2, v3 bitop3:0xf6
	v_and_b32_e32 v1, 0x38000, v1
	v_lshlrev_b32_e32 v2, 11, v10
	v_or3_b32 v1, v8, v1, v2
	v_add_u32_e32 v136, v1, v9
	v_lshlrev_b32_e32 v1, 4, v12
	s_waitcnt vmcnt(6)
	s_cmpk_lt_u32 s5, 0x100
	v_and_b32_e32 v1, 0x78000, v1
	v_bitop3_b32 v0, v0, s15, v3 bitop3:0xde
	s_cselect_b64 s[14:15], -1, 0
	v_or3_b32 v1, v8, v1, v2
	s_add_i32 s50, 0, 0x10000
	s_add_i32 s51, 0, 0x14000
	s_mov_b32 s49, s92
	v_or_b32_e32 v146, s18, v11
	v_mov_b32_e32 v137, v131
	v_add_u32_e32 v138, v1, v9
	v_mov_b32_e32 v139, v131
	v_mov_b64_e32 v[140:141], 0x800
	v_mov_b64_e32 v[142:143], 0x7ff
	v_add_u32_e32 v147, s50, v145
	v_add_u32_e32 v148, s51, v145
	v_add_u32_e32 v149, 0, v0
	s_mov_b64 s[16:17], 0x804000
	s_mov_b32 s52, 0x4000
	s_mov_b64 s[18:19], 0x804800
	s_mov_b32 s53, 0x4800
	s_mov_b64 s[20:21], 0x805000
	s_mov_b32 s54, 0x5000
	s_mov_b64 s[22:23], 0x805800
	s_mov_b32 s55, 0x5800
	s_mov_b64 s[98:99], 0x800000
	s_barrier
	s_branch .LBB0_870

.LBB0_880:
	v_lshl_add_u32 v150, s34, 8, v144
	v_max_f32_e32 v124, v124, v124
	v_max_f32_e32 v120, v120, v120
	v_max_f32_e32 v125, v125, v125
	v_max_f32_e32 v121, v121, v121
	v_max_f32_e32 v126, v126, v126
	v_max_f32_e32 v127, v127, v127
	v_lshl_or_b32 v152, s56, 8, v146
	v_ashrrev_i32_e32 v151, 31, v150
	v_max_f32_e32 v124, 0, v124
	v_max_f32_e32 v120, 0, v120
	v_max_f32_e32 v125, 0, v125
	v_max_f32_e32 v121, 0, v121
	v_max_f32_e32 v126, 0, v126
	v_max_f32_e32 v122, v122, v122
	v_max_f32_e32 v127, 0, v127
	v_max_f32_e32 v123, v123, v123
	v_ashrrev_i32_e32 v153, 31, v152
	v_lshlrev_b64 v[154:155], 7, v[150:151]
	v_pk_mul_f32 v[124:125], v[124:125], v[124:125]
	v_pk_mul_f32 v[120:121], v[120:121], v[120:121]
	v_max_f32_e32 v122, 0, v122
	v_max_f32_e32 v123, 0, v123
	v_pk_mul_f32 v[126:127], v[126:127], v[126:127]
	v_pk_mul_f32 v[156:157], v[122:123], v[122:123]
	v_cvt_pk_bf16_f32 v122, v124, v125
	v_cvt_pk_bf16_f32 v123, v126, v127
	v_cvt_pk_bf16_f32 v124, v120, v121
	v_lshl_add_u64 v[120:121], s[78:79], 0, v[154:155]
	v_and_b32_e32 v126, 0xfc0, v152
	v_and_b32_e32 v127, 63, v152
	v_lshlrev_b32_e32 v126, 16, v126
	v_lshl_or_b32 v126, v127, 1, v126
	v_mov_b32_e32 v127, 0
	v_max_f32_e32 v112, v112, v112
	v_max_f32_e32 v113, v113, v113
	v_cvt_pk_bf16_f32 v125, v156, v157
	v_lshl_add_u64 v[120:121], v[120:121], 0, v[126:127]
	v_max_f32_e32 v112, 0, v112
	v_max_f32_e32 v113, 0, v113
	global_store_dwordx4 v[120:121], v[122:125], off
	v_max_f32_e32 v116, v116, v116
	v_max_f32_e32 v117, v117, v117
	v_pk_mul_f32 v[122:123], v[112:113], v[112:113]
	v_max_f32_e32 v113, v114, v114
	v_max_f32_e32 v112, v118, v118
	v_max_f32_e32 v114, 0, v113
	v_max_f32_e32 v113, v119, v119
	v_max_f32_e32 v115, v115, v115
	v_max_f32_e32 v116, 0, v116
	v_max_f32_e32 v117, 0, v117
	v_max_f32_e32 v112, 0, v112
	v_max_f32_e32 v113, 0, v113
	v_max_f32_e32 v115, 0, v115
	v_pk_mul_f32 v[116:117], v[116:117], v[116:117]
	v_pk_mul_f32 v[118:119], v[112:113], v[112:113]
	v_pk_mul_f32 v[124:125], v[114:115], v[114:115]
	v_max_f32_e32 v104, v104, v104
	v_max_f32_e32 v105, v105, v105
	v_cvt_pk_bf16_f32 v112, v116, v117
	v_cvt_pk_bf16_f32 v113, v118, v119
	v_cvt_pk_bf16_f32 v114, v122, v123
	v_cvt_pk_bf16_f32 v115, v124, v125
	v_max_f32_e32 v104, 0, v104
	v_max_f32_e32 v105, 0, v105
	v_lshl_add_u64 v[200:201], v[120:121], 0, s[98:99]
	global_store_dwordx4 v[200:201], v[112:115], off
	v_max_f32_e32 v108, v108, v108
	v_max_f32_e32 v109, v109, v109
	v_or_b32_e32 v112, 16, v150
	v_pk_mul_f32 v[114:115], v[104:105], v[104:105]
	v_max_f32_e32 v105, v106, v106
	v_ashrrev_i32_e32 v113, 31, v112
	v_max_f32_e32 v108, 0, v108
	v_max_f32_e32 v109, 0, v109
	v_max_f32_e32 v104, v110, v110
	v_max_f32_e32 v106, 0, v105
	v_max_f32_e32 v105, v111, v111
	v_max_f32_e32 v107, v107, v107
	v_lshlrev_b64 v[112:113], 7, v[112:113]
	v_pk_mul_f32 v[108:109], v[108:109], v[108:109]
	v_max_f32_e32 v104, 0, v104
	v_max_f32_e32 v105, 0, v105
	v_max_f32_e32 v107, 0, v107
	v_pk_mul_f32 v[110:111], v[104:105], v[104:105]
	v_pk_mul_f32 v[116:117], v[106:107], v[106:107]
	v_cvt_pk_bf16_f32 v104, v108, v109
	v_lshl_add_u64 v[108:109], s[78:79], 0, v[112:113]
	v_max_f32_e32 v96, v96, v96
	v_max_f32_e32 v97, v97, v97
	v_cvt_pk_bf16_f32 v105, v110, v111
	v_cvt_pk_bf16_f32 v106, v114, v115
	v_cvt_pk_bf16_f32 v107, v116, v117
	v_lshl_add_u64 v[108:109], v[108:109], 0, v[126:127]
	v_max_f32_e32 v96, 0, v96
	v_max_f32_e32 v97, 0, v97
	global_store_dwordx4 v[108:109], v[104:107], off
	v_max_f32_e32 v100, v100, v100
	v_max_f32_e32 v101, v101, v101
	v_pk_mul_f32 v[104:105], v[96:97], v[96:97]
	v_max_f32_e32 v97, v98, v98
	v_max_f32_e32 v96, v102, v102
	v_max_f32_e32 v98, 0, v97
	v_max_f32_e32 v97, v103, v103
	v_max_f32_e32 v99, v99, v99
	v_max_f32_e32 v100, 0, v100
	v_max_f32_e32 v101, 0, v101
	v_max_f32_e32 v96, 0, v96
	v_max_f32_e32 v97, 0, v97
	v_max_f32_e32 v99, 0, v99
	v_pk_mul_f32 v[100:101], v[100:101], v[100:101]
	v_pk_mul_f32 v[102:103], v[96:97], v[96:97]
	v_pk_mul_f32 v[106:107], v[98:99], v[98:99]
	v_max_f32_e32 v88, v88, v88
	v_max_f32_e32 v89, v89, v89
	v_cvt_pk_bf16_f32 v96, v100, v101
	v_cvt_pk_bf16_f32 v97, v102, v103
	v_cvt_pk_bf16_f32 v98, v104, v105
	v_cvt_pk_bf16_f32 v99, v106, v107
	v_max_f32_e32 v88, 0, v88
	v_max_f32_e32 v89, 0, v89
	v_lshl_add_u64 v[202:203], v[108:109], 0, s[98:99]
	global_store_dwordx4 v[202:203], v[96:99], off
	v_max_f32_e32 v92, v92, v92
	v_max_f32_e32 v93, v93, v93
	v_or_b32_e32 v96, 32, v150
	v_pk_mul_f32 v[98:99], v[88:89], v[88:89]
	v_max_f32_e32 v89, v90, v90
	v_ashrrev_i32_e32 v97, 31, v96
	v_max_f32_e32 v92, 0, v92
	v_max_f32_e32 v93, 0, v93
	v_max_f32_e32 v88, v94, v94
	v_max_f32_e32 v90, 0, v89
	v_max_f32_e32 v89, v95, v95
	v_max_f32_e32 v91, v91, v91
	v_lshlrev_b64 v[96:97], 7, v[96:97]
	v_pk_mul_f32 v[92:93], v[92:93], v[92:93]
	v_max_f32_e32 v88, 0, v88
	v_max_f32_e32 v89, 0, v89
	v_max_f32_e32 v91, 0, v91
	v_pk_mul_f32 v[94:95], v[88:89], v[88:89]
	v_pk_mul_f32 v[100:101], v[90:91], v[90:91]
	v_cvt_pk_bf16_f32 v88, v92, v93
	v_lshl_add_u64 v[92:93], s[78:79], 0, v[96:97]
	v_max_f32_e32 v80, v80, v80
	v_max_f32_e32 v81, v81, v81
	v_cvt_pk_bf16_f32 v89, v94, v95
	v_cvt_pk_bf16_f32 v90, v98, v99
	v_cvt_pk_bf16_f32 v91, v100, v101
	v_lshl_add_u64 v[92:93], v[92:93], 0, v[126:127]
	v_max_f32_e32 v80, 0, v80
	v_max_f32_e32 v81, 0, v81
	global_store_dwordx4 v[92:93], v[88:91], off
	v_max_f32_e32 v84, v84, v84
	v_max_f32_e32 v85, v85, v85
	v_pk_mul_f32 v[88:89], v[80:81], v[80:81]
	v_max_f32_e32 v81, v82, v82
	v_max_f32_e32 v80, v86, v86
	v_max_f32_e32 v82, 0, v81
	v_max_f32_e32 v81, v87, v87
	v_max_f32_e32 v83, v83, v83
	v_max_f32_e32 v84, 0, v84
	v_max_f32_e32 v85, 0, v85
	v_max_f32_e32 v80, 0, v80
	v_max_f32_e32 v81, 0, v81
	v_max_f32_e32 v83, 0, v83
	v_pk_mul_f32 v[84:85], v[84:85], v[84:85]
	v_pk_mul_f32 v[86:87], v[80:81], v[80:81]
	v_pk_mul_f32 v[90:91], v[82:83], v[82:83]
	v_max_f32_e32 v72, v72, v72
	v_max_f32_e32 v73, v73, v73
	v_cvt_pk_bf16_f32 v80, v84, v85
	v_cvt_pk_bf16_f32 v81, v86, v87
	v_cvt_pk_bf16_f32 v82, v88, v89
	v_cvt_pk_bf16_f32 v83, v90, v91
	v_max_f32_e32 v72, 0, v72
	v_max_f32_e32 v73, 0, v73
	v_lshl_add_u64 v[204:205], v[92:93], 0, s[98:99]
	global_store_dwordx4 v[204:205], v[80:83], off
	v_max_f32_e32 v76, v76, v76
	v_max_f32_e32 v77, v77, v77
	v_or_b32_e32 v80, 48, v150
	v_pk_mul_f32 v[82:83], v[72:73], v[72:73]
	v_max_f32_e32 v73, v74, v74
	v_ashrrev_i32_e32 v81, 31, v80
	v_max_f32_e32 v76, 0, v76
	v_max_f32_e32 v77, 0, v77
	v_max_f32_e32 v72, v78, v78
	v_max_f32_e32 v74, 0, v73
	v_max_f32_e32 v73, v79, v79
	v_max_f32_e32 v75, v75, v75
	v_lshlrev_b64 v[80:81], 7, v[80:81]
	v_pk_mul_f32 v[76:77], v[76:77], v[76:77]
	v_max_f32_e32 v72, 0, v72
	v_max_f32_e32 v73, 0, v73
	v_max_f32_e32 v75, 0, v75
	v_pk_mul_f32 v[78:79], v[72:73], v[72:73]
	v_pk_mul_f32 v[84:85], v[74:75], v[74:75]
	v_cvt_pk_bf16_f32 v72, v76, v77
	v_lshl_add_u64 v[76:77], s[78:79], 0, v[80:81]
	v_max_f32_e32 v64, v64, v64
	v_max_f32_e32 v65, v65, v65
	v_cvt_pk_bf16_f32 v73, v78, v79
	v_cvt_pk_bf16_f32 v74, v82, v83
	v_cvt_pk_bf16_f32 v75, v84, v85
	v_lshl_add_u64 v[76:77], v[76:77], 0, v[126:127]
	v_max_f32_e32 v64, 0, v64
	v_max_f32_e32 v65, 0, v65
	global_store_dwordx4 v[76:77], v[72:75], off
	v_max_f32_e32 v68, v68, v68
	v_max_f32_e32 v69, v69, v69
	v_pk_mul_f32 v[72:73], v[64:65], v[64:65]
	v_max_f32_e32 v65, v66, v66
	v_max_f32_e32 v64, v70, v70
	v_max_f32_e32 v66, 0, v65
	v_max_f32_e32 v65, v71, v71
	v_max_f32_e32 v67, v67, v67
	v_max_f32_e32 v68, 0, v68
	v_max_f32_e32 v69, 0, v69
	v_max_f32_e32 v64, 0, v64
	v_max_f32_e32 v65, 0, v65
	v_max_f32_e32 v67, 0, v67
	v_pk_mul_f32 v[68:69], v[68:69], v[68:69]
	v_pk_mul_f32 v[70:71], v[64:65], v[64:65]
	v_pk_mul_f32 v[74:75], v[66:67], v[66:67]
	v_max_f32_e32 v56, v56, v56
	v_max_f32_e32 v57, v57, v57
	v_cvt_pk_bf16_f32 v64, v68, v69
	v_cvt_pk_bf16_f32 v65, v70, v71
	v_cvt_pk_bf16_f32 v66, v72, v73
	v_cvt_pk_bf16_f32 v67, v74, v75
	v_max_f32_e32 v56, 0, v56
	v_max_f32_e32 v57, 0, v57
	v_lshl_add_u64 v[206:207], v[76:77], 0, s[98:99]
	global_store_dwordx4 v[206:207], v[64:67], off
	v_max_f32_e32 v60, v60, v60
	v_max_f32_e32 v61, v61, v61
	v_pk_mul_f32 v[64:65], v[56:57], v[56:57]
	v_max_f32_e32 v57, v58, v58
	v_max_f32_e32 v56, v62, v62
	v_max_f32_e32 v58, 0, v57
	v_max_f32_e32 v57, v63, v63
	v_max_f32_e32 v56, 0, v56
	v_max_f32_e32 v57, 0, v57
	v_max_f32_e32 v59, v59, v59
	v_max_f32_e32 v60, 0, v60
	v_max_f32_e32 v61, 0, v61
	v_max_f32_e32 v59, 0, v59
	v_pk_mul_f32 v[62:63], v[56:57], v[56:57]
	v_pk_mul_f32 v[60:61], v[60:61], v[60:61]
	v_pk_mul_f32 v[66:67], v[58:59], v[58:59]
	v_cvt_pk_bf16_f32 v57, v62, v63
	v_add_co_u32_e32 v62, vcc, s52, v120
	v_max_f32_e32 v48, v48, v48
	v_max_f32_e32 v49, v49, v49
	v_cvt_pk_bf16_f32 v56, v60, v61
	v_cvt_pk_bf16_f32 v58, v64, v65
	v_cvt_pk_bf16_f32 v59, v66, v67
	v_addc_co_u32_e32 v63, vcc, 0, v121, vcc
	v_max_f32_e32 v48, 0, v48
	v_max_f32_e32 v49, 0, v49
	global_store_dwordx4 v[62:63], v[56:59], off
	v_max_f32_e32 v52, v52, v52
	v_max_f32_e32 v53, v53, v53
	v_pk_mul_f32 v[56:57], v[48:49], v[48:49]
	v_max_f32_e32 v49, v50, v50
	v_max_f32_e32 v48, v54, v54
	v_max_f32_e32 v50, 0, v49
	v_max_f32_e32 v49, v55, v55
	v_max_f32_e32 v51, v51, v51
	v_max_f32_e32 v52, 0, v52
	v_max_f32_e32 v53, 0, v53
	v_max_f32_e32 v48, 0, v48
	v_max_f32_e32 v49, 0, v49
	v_max_f32_e32 v51, 0, v51
	v_pk_mul_f32 v[52:53], v[52:53], v[52:53]
	v_pk_mul_f32 v[54:55], v[48:49], v[48:49]
	v_pk_mul_f32 v[58:59], v[50:51], v[50:51]
	v_max_f32_e32 v40, v40, v40
	v_max_f32_e32 v41, v41, v41
	v_lshl_add_u64 v[60:61], v[120:121], 0, s[16:17]
	v_cvt_pk_bf16_f32 v48, v52, v53
	v_cvt_pk_bf16_f32 v49, v54, v55
	v_cvt_pk_bf16_f32 v50, v56, v57
	v_cvt_pk_bf16_f32 v51, v58, v59
	v_max_f32_e32 v40, 0, v40
	v_max_f32_e32 v41, 0, v41
	global_store_dwordx4 v[60:61], v[48:51], off
	v_max_f32_e32 v44, v44, v44
	v_max_f32_e32 v45, v45, v45
	v_pk_mul_f32 v[48:49], v[40:41], v[40:41]
	v_max_f32_e32 v41, v42, v42
	v_max_f32_e32 v40, v46, v46
	v_max_f32_e32 v42, 0, v41
	v_max_f32_e32 v41, v47, v47
	v_max_f32_e32 v40, 0, v40
	v_max_f32_e32 v41, 0, v41
	v_max_f32_e32 v43, v43, v43
	v_max_f32_e32 v44, 0, v44
	v_max_f32_e32 v45, 0, v45
	v_max_f32_e32 v43, 0, v43
	v_pk_mul_f32 v[46:47], v[40:41], v[40:41]
	v_pk_mul_f32 v[44:45], v[44:45], v[44:45]
	v_pk_mul_f32 v[50:51], v[42:43], v[42:43]
	v_cvt_pk_bf16_f32 v41, v46, v47
	v_add_co_u32_e32 v46, vcc, s53, v120
	v_max_f32_e32 v32, v32, v32
	v_max_f32_e32 v33, v33, v33
	v_cvt_pk_bf16_f32 v40, v44, v45
	v_cvt_pk_bf16_f32 v42, v48, v49
	v_cvt_pk_bf16_f32 v43, v50, v51
	v_addc_co_u32_e32 v47, vcc, 0, v121, vcc
	v_max_f32_e32 v32, 0, v32
	v_max_f32_e32 v33, 0, v33
	global_store_dwordx4 v[46:47], v[40:43], off
	v_max_f32_e32 v36, v36, v36
	v_max_f32_e32 v37, v37, v37
	v_pk_mul_f32 v[40:41], v[32:33], v[32:33]
	v_max_f32_e32 v33, v34, v34
	v_max_f32_e32 v32, v38, v38
	v_max_f32_e32 v34, 0, v33
	v_max_f32_e32 v33, v39, v39
	v_max_f32_e32 v35, v35, v35
	v_max_f32_e32 v36, 0, v36
	v_max_f32_e32 v37, 0, v37
	v_max_f32_e32 v32, 0, v32
	v_max_f32_e32 v33, 0, v33
	v_max_f32_e32 v35, 0, v35
	v_pk_mul_f32 v[36:37], v[36:37], v[36:37]
	v_pk_mul_f32 v[38:39], v[32:33], v[32:33]
	v_pk_mul_f32 v[42:43], v[34:35], v[34:35]
	v_max_f32_e32 v24, v24, v24
	v_max_f32_e32 v25, v25, v25
	v_lshl_add_u64 v[44:45], v[120:121], 0, s[18:19]
	v_cvt_pk_bf16_f32 v32, v36, v37
	v_cvt_pk_bf16_f32 v33, v38, v39
	v_cvt_pk_bf16_f32 v34, v40, v41
	v_cvt_pk_bf16_f32 v35, v42, v43
	v_max_f32_e32 v24, 0, v24
	v_max_f32_e32 v25, 0, v25
	global_store_dwordx4 v[44:45], v[32:35], off
	v_max_f32_e32 v28, v28, v28
	v_max_f32_e32 v29, v29, v29
	v_pk_mul_f32 v[32:33], v[24:25], v[24:25]
	v_max_f32_e32 v25, v26, v26
	v_max_f32_e32 v24, v30, v30
	v_max_f32_e32 v26, 0, v25
	v_max_f32_e32 v25, v31, v31
	v_max_f32_e32 v24, 0, v24
	v_max_f32_e32 v25, 0, v25
	v_max_f32_e32 v27, v27, v27
	v_max_f32_e32 v28, 0, v28
	v_max_f32_e32 v29, 0, v29
	v_max_f32_e32 v27, 0, v27
	v_pk_mul_f32 v[30:31], v[24:25], v[24:25]
	v_pk_mul_f32 v[28:29], v[28:29], v[28:29]
	v_pk_mul_f32 v[34:35], v[26:27], v[26:27]
	v_cvt_pk_bf16_f32 v25, v30, v31
	v_add_co_u32_e32 v30, vcc, s54, v120
	v_max_f32_e32 v16, v16, v16
	v_max_f32_e32 v17, v17, v17
	v_cvt_pk_bf16_f32 v24, v28, v29
	v_cvt_pk_bf16_f32 v26, v32, v33
	v_cvt_pk_bf16_f32 v27, v34, v35
	v_addc_co_u32_e32 v31, vcc, 0, v121, vcc
	v_max_f32_e32 v16, 0, v16
	v_max_f32_e32 v17, 0, v17
	global_store_dwordx4 v[30:31], v[24:27], off
	v_max_f32_e32 v20, v20, v20
	v_max_f32_e32 v21, v21, v21
	v_pk_mul_f32 v[24:25], v[16:17], v[16:17]
	v_max_f32_e32 v17, v18, v18
	v_max_f32_e32 v16, v22, v22
	v_max_f32_e32 v18, 0, v17
	v_max_f32_e32 v17, v23, v23
	v_max_f32_e32 v19, v19, v19
	v_max_f32_e32 v20, 0, v20
	v_max_f32_e32 v21, 0, v21
	v_max_f32_e32 v16, 0, v16
	v_max_f32_e32 v17, 0, v17
	v_max_f32_e32 v19, 0, v19
	v_pk_mul_f32 v[20:21], v[20:21], v[20:21]
	v_pk_mul_f32 v[22:23], v[16:17], v[16:17]
	v_pk_mul_f32 v[26:27], v[18:19], v[18:19]
	v_max_f32_e32 v8, v8, v8
	v_max_f32_e32 v9, v9, v9
	v_lshl_add_u64 v[28:29], v[120:121], 0, s[20:21]
	v_cvt_pk_bf16_f32 v16, v20, v21
	v_cvt_pk_bf16_f32 v17, v22, v23
	v_cvt_pk_bf16_f32 v18, v24, v25
	v_cvt_pk_bf16_f32 v19, v26, v27
	v_max_f32_e32 v8, 0, v8
	v_max_f32_e32 v9, 0, v9
	global_store_dwordx4 v[28:29], v[16:19], off
	v_max_f32_e32 v12, v12, v12
	v_max_f32_e32 v13, v13, v13
	v_pk_mul_f32 v[16:17], v[8:9], v[8:9]
	v_max_f32_e32 v9, v10, v10
	v_max_f32_e32 v8, v14, v14
	v_max_f32_e32 v10, 0, v9
	v_max_f32_e32 v9, v15, v15
	v_max_f32_e32 v8, 0, v8
	v_max_f32_e32 v9, 0, v9
	v_max_f32_e32 v11, v11, v11
	v_max_f32_e32 v12, 0, v12
	v_max_f32_e32 v13, 0, v13
	v_max_f32_e32 v11, 0, v11
	v_pk_mul_f32 v[14:15], v[8:9], v[8:9]
	v_pk_mul_f32 v[12:13], v[12:13], v[12:13]
	v_pk_mul_f32 v[18:19], v[10:11], v[10:11]
	v_cvt_pk_bf16_f32 v9, v14, v15
	v_add_co_u32_e32 v14, vcc, s55, v120
	v_max_f32_e32 v0, v0, v0
	v_max_f32_e32 v1, v1, v1
	v_cvt_pk_bf16_f32 v8, v12, v13
	v_cvt_pk_bf16_f32 v10, v16, v17
	v_cvt_pk_bf16_f32 v11, v18, v19
	v_addc_co_u32_e32 v15, vcc, 0, v121, vcc
	v_max_f32_e32 v0, 0, v0
	v_max_f32_e32 v1, 0, v1
	global_store_dwordx4 v[14:15], v[8:11], off
	v_max_f32_e32 v4, v4, v4
	v_max_f32_e32 v5, v5, v5
	v_pk_mul_f32 v[8:9], v[0:1], v[0:1]
	v_max_f32_e32 v1, v2, v2
	v_max_f32_e32 v0, v6, v6
	v_max_f32_e32 v2, 0, v1
	v_max_f32_e32 v1, v7, v7
	v_max_f32_e32 v3, v3, v3
	v_max_f32_e32 v4, 0, v4
	v_max_f32_e32 v5, 0, v5
	v_max_f32_e32 v0, 0, v0
	v_max_f32_e32 v1, 0, v1
	v_max_f32_e32 v3, 0, v3
	v_pk_mul_f32 v[4:5], v[4:5], v[4:5]
	v_pk_mul_f32 v[6:7], v[0:1], v[0:1]
	v_pk_mul_f32 v[10:11], v[2:3], v[2:3]
	v_lshl_add_u64 v[12:13], v[120:121], 0, s[22:23]
	v_cvt_pk_bf16_f32 v0, v4, v5
	v_cvt_pk_bf16_f32 v1, v6, v7
	v_cvt_pk_bf16_f32 v2, v8, v9
	v_cvt_pk_bf16_f32 v3, v10, v11
	s_andn2_b64 vcc, exec, s[4:5]
	s_mov_b64 s[4:5], -1
	global_store_dwordx4 v[12:13], v[0:3], off
	s_cbranch_vccnz .LBB0_869
	s_andn2_b64 vcc, exec, s[6:7]
	s_cbranch_vccnz .LBB0_868
	s_barrier
	s_branch .LBB0_868

.LBB0_941:
	s_andn2_b64 vcc, exec, s[4:5]
	s_cbranch_vccnz .LBB0_977
	s_waitcnt vmcnt(0)
	v_lshrrev_b32_e32 v2, 1, v220
	v_lshrrev_b32_e32 v3, 5, v220
	v_and_b32_e32 v2, 24, v2
	v_and_b32_e32 v3, 4, v3
	v_bfe_u32 v4, v220, 2, 2
	v_lshlrev_b32_e32 v0, 4, v220
	v_and_b32_e32 v1, 32, v220
	v_bfe_u32 v10, v220, 2, 4
	v_or3_b32 v2, v3, v4, v2
	v_lshrrev_b32_e32 v3, 3, v220
	s_movk_i32 s3, 0x70
	v_bitop3_b32 v8, v0, v1, 48 bitop3:0x6c
	v_and_b32_e32 v9, 64, v220
	v_and_or_b32 v4, v3, s3, v10
	s_movk_i32 s3, 0x60
	v_add_u32_e32 v11, 0x2000, v0
	v_or_b32_e32 v1, v8, v9
	v_and_or_b32 v3, v3, s3, v2
	v_lshrrev_b32_e32 v0, 7, v11
	s_movk_i32 s3, 0xf0
	v_lshl_or_b32 v130, v3, 13, v1
	v_and_or_b32 v3, v0, s3, v10
	s_movk_i32 s3, 0xe0
	s_lshr_b32 s4, s6, 6
	s_ashr_i32 s31, s30, 31
	s_ashr_i32 s15, s14, 31
	v_and_or_b32 v0, v0, s3, v2
	s_lshr_b32 s7, s6, 8
	s_lshl_b32 s3, s4, 10
	s_lshl_b64 s[16:17], s[30:31], 15
	s_lshl_b64 s[18:19], s[14:15], 21
	s_add_u32 s36, s70, s18
	s_addc_u32 s37, s71, s19
	s_add_i32 s33, s3, 0
	s_add_i32 m0, s33, 0x10000
	v_lshl_or_b32 v134, v0, 13, v1
	global_load_lds_dwordx4 v130, s[36:37]
	s_add_i32 m0, s33, 0x12000
	s_add_u32 s18, s36, 0x100000
	global_load_lds_dwordx4 v134, s[36:37]
	s_addc_u32 s19, s37, 0
	s_add_i32 m0, s33, 0x14000
	v_lshl_or_b32 v128, v4, 7, v1
	global_load_lds_dwordx4 v130, s[18:19]
	s_add_i32 m0, s33, 0x16000
	s_add_u32 s34, s78, s16
	s_addc_u32 s35, s79, s17
	s_add_i32 s40, s33, 0x2000
	global_load_lds_dwordx4 v134, s[18:19]
	s_mov_b32 m0, s33
	s_add_u32 s16, s34, 0x4000
	v_lshl_or_b32 v132, v3, 7, v1
	global_load_lds_dwordx4 v128, s[34:35]
	s_mov_b32 m0, s40
	s_addc_u32 s17, s35, 0
	s_add_i32 s41, s33, 0x4000
	global_load_lds_dwordx4 v132, s[34:35]
	s_mov_b32 m0, s41
	s_add_i32 s42, s33, 0x6000
	global_load_lds_dwordx4 v128, s[16:17]
	s_mov_b32 m0, s42
	v_mov_b32_e32 v131, 0
	global_load_lds_dwordx4 v132, s[16:17]
	v_mov_b32_e32 v135, v131
	v_mov_b32_e32 v129, v131
	v_mov_b32_e32 v133, v131
	s_cmp_eq_u32 s7, 1
	s_mov_b32 s15, 0
	v_lshl_add_u64 v[6:7], s[36:37], 0, v[130:131]
	s_waitcnt lgkmcnt(0)
	v_lshl_add_u64 v[4:5], s[36:37], 0, v[134:135]
	v_lshl_add_u64 v[0:1], s[34:35], 0, v[128:129]
	s_cselect_b64 s[16:17], -1, 0
	s_cmp_lg_u32 s7, 1
	v_lshl_add_u64 v[2:3], s[34:35], 0, v[132:133]
	s_cbranch_scc1 .LBB0_944
	s_barrier
.LBB0_944:
	s_mov_b64 s[18:19], 0x80
	s_mov_b64 s[98:99], 0x400000
	s_and_b32 s45, s4, 3
	s_add_i32 m0, s33, 0x18000
	v_lshl_add_u64 v[6:7], v[6:7], 0, s[18:19]
	s_ashr_i32 s43, s92, 31
	s_ashr_i32 s44, s2, 31
	s_lshl_b32 s20, s7, 13
	s_lshl_b32 s21, s45, 12
	s_waitcnt vmcnt(2)
	s_barrier
	global_load_lds_dwordx4 v[6:7], off
	v_lshl_add_u64 v[4:5], v[4:5], 0, s[18:19]
	s_add_i32 m0, s33, 0x1a000
	s_add_i32 s46, s33, 0x8000
	s_add_i32 s47, s33, 0xa000
	global_load_lds_dwordx4 v[4:5], off
	v_lshl_add_u64 v[0:1], v[0:1], 0, s[98:99]
	s_mov_b32 m0, s46
	s_add_u32 s4, s36, 0x100080
	global_load_lds_dwordx4 v[0:1], off
	v_lshl_add_u64 v[0:1], v[2:3], 0, s[98:99]
	s_mov_b32 m0, s47
	s_addc_u32 s5, s37, 0
	global_load_lds_dwordx4 v[0:1], off
	s_add_i32 m0, s33, 0x1c000
	v_lshl_add_u64 v[0:1], s[4:5], 0, v[130:131]
	global_load_lds_dwordx4 v[0:1], off
	v_lshl_add_u64 v[0:1], s[4:5], 0, v[134:135]
	s_add_i32 m0, s33, 0x1e000
	v_lshlrev_b32_e32 v4, 6, v220
	global_load_lds_dwordx4 v[0:1], off
	v_bfe_u32 v0, v220, 4, 2
	v_and_b32_e32 v1, 15, v220
	v_lshlrev_b32_e32 v3, 4, v0
	s_movk_i32 s4, 0x3c0
	v_lshlrev_b32_e32 v2, 3, v0
	v_and_or_b32 v4, v4, s4, v3
	v_cmp_eq_u32_e64 s[4:5], 0, v0
	v_lshl_or_b32 v148, s7, 6, v1
	v_lshl_or_b32 v0, v1, 6, v3
	v_lshlrev_b32_e32 v1, 4, v220
	v_lshl_or_b32 v150, s45, 5, v2
	v_and_b32_e32 v1, 0x3800, v1
	v_lshlrev_b32_e32 v2, 7, v10
	v_lshlrev_b32_e32 v5, 2, v220
	v_or3_b32 v1, v8, v1, v2
	v_and_b32_e32 v5, 32, v5
	v_add_u32_e32 v136, v1, v9
	v_mov_b32_e32 v1, v11
	v_bitop3_b32 v0, v0, s20, v5 bitop3:0xde
	s_waitcnt vmcnt(6)
	s_cmpk_lt_u32 s6, 0x100
	v_and_b32_e32 v1, 0x7800, v1
	v_bitop3_b32 v149, s21, v4, v5 bitop3:0xf6
	s_cselect_b64 s[20:21], -1, 0
	v_or3_b32 v1, v8, v1, v2
	s_add_i32 s49, 0, 0x10000
	s_add_i32 s50, 0, 0x14000
	v_add_u32_e32 v153, 0, v0
	v_mbcnt_lo_u32_b32 v0, -1, 0
	s_mov_b32 s48, s92
	v_mov_b32_e32 v137, v131
	v_add_u32_e32 v138, v1, v9
	v_mov_b32_e32 v139, v131
	v_mov_b64_e32 v[140:141], 0x200
	v_mov_b64_e32 v[142:143], 0x1ff
	v_add_u32_e32 v151, s49, v149
	v_add_u32_e32 v152, s50, v149
	v_mbcnt_hi_u32_b32 v154, -1, v0
	s_mov_b32 s51, 0
	s_barrier
	s_branch .LBB0_947

.LBB0_953:
	s_ashr_i32 s25, s24, 31
	s_lshl_b64 s[26:27], s[24:25], 15
	s_add_u32 s26, s78, s26
	s_addc_u32 s27, s79, s27
	s_and_b64 s[28:29], s[6:7], exec
	s_cselect_b32 s25, s27, s35
	s_cselect_b32 s31, s26, s34
	s_ashr_i32 s23, s22, 31
	s_lshl_b64 s[28:29], s[22:23], 21
	s_add_u32 s28, s70, s28
	s_addc_u32 s29, s71, s29
	s_and_b64 s[38:39], s[6:7], exec
	s_cselect_b32 s23, s29, s37
	s_cselect_b32 s52, s28, s36
	s_add_u32 s34, s34, 0x404000
	s_addc_u32 s35, s35, 0
	s_add_u32 s53, s36, 0x100
	v_mov_b32_e32 v0, 0
	s_addc_u32 s54, s37, 0
	s_mov_b32 s55, -2
	v_mov_b32_e32 v1, v0
	v_mov_b32_e32 v2, v0
	v_mov_b32_e32 v3, v0
	v_mov_b32_e32 v4, v0
	s_waitcnt lgkmcnt(0)
	v_mov_b32_e32 v5, v0
	v_mov_b32_e32 v6, v0
	v_mov_b32_e32 v7, v0
	v_mov_b32_e32 v16, v0
	v_mov_b32_e32 v17, v0
	v_mov_b32_e32 v18, v0
	v_mov_b32_e32 v19, v0
	v_mov_b32_e32 v20, v0
	v_mov_b32_e32 v21, v0
	v_mov_b32_e32 v22, v0
	v_mov_b32_e32 v23, v0
	v_mov_b32_e32 v32, v0
	v_mov_b32_e32 v33, v0
	v_mov_b32_e32 v34, v0
	v_mov_b32_e32 v35, v0
	v_mov_b32_e32 v36, v0
	v_mov_b32_e32 v37, v0
	v_mov_b32_e32 v38, v0
	v_mov_b32_e32 v39, v0
	v_mov_b32_e32 v48, v0
	v_mov_b32_e32 v49, v0
	v_mov_b32_e32 v50, v0
	v_mov_b32_e32 v51, v0
	v_mov_b32_e32 v52, v0
	v_mov_b32_e32 v53, v0
	v_mov_b32_e32 v54, v0
	v_mov_b32_e32 v55, v0
	v_mov_b32_e32 v8, v0
	v_mov_b32_e32 v9, v0
	v_mov_b32_e32 v10, v0
	v_mov_b32_e32 v11, v0
	v_mov_b32_e32 v12, v0
	v_mov_b32_e32 v13, v0
	v_mov_b32_e32 v14, v0
	v_mov_b32_e32 v15, v0
	v_mov_b32_e32 v24, v0
	v_mov_b32_e32 v25, v0
	v_mov_b32_e32 v26, v0
	v_mov_b32_e32 v27, v0
	v_mov_b32_e32 v28, v0
	v_mov_b32_e32 v29, v0
	v_mov_b32_e32 v30, v0
	v_mov_b32_e32 v31, v0
	v_mov_b32_e32 v40, v0
	v_mov_b32_e32 v41, v0
	v_mov_b32_e32 v42, v0
	v_mov_b32_e32 v43, v0
	v_mov_b32_e32 v44, v0
	v_mov_b32_e32 v45, v0
	v_mov_b32_e32 v46, v0
	v_mov_b32_e32 v47, v0
	v_mov_b32_e32 v56, v0
	v_mov_b32_e32 v57, v0
	v_mov_b32_e32 v58, v0
	v_mov_b32_e32 v59, v0
	v_mov_b32_e32 v60, v0
	v_mov_b32_e32 v61, v0
	v_mov_b32_e32 v62, v0
	v_mov_b32_e32 v63, v0
	v_mov_b32_e32 v64, v0
	v_mov_b32_e32 v65, v0
	v_mov_b32_e32 v66, v0
	v_mov_b32_e32 v67, v0
	v_mov_b32_e32 v68, v0
	v_mov_b32_e32 v69, v0
	v_mov_b32_e32 v70, v0
	v_mov_b32_e32 v71, v0
	v_mov_b32_e32 v80, v0
	v_mov_b32_e32 v81, v0
	v_mov_b32_e32 v82, v0
	v_mov_b32_e32 v83, v0
	v_mov_b32_e32 v84, v0
	v_mov_b32_e32 v85, v0
	v_mov_b32_e32 v86, v0
	v_mov_b32_e32 v87, v0
	v_mov_b32_e32 v96, v0
	v_mov_b32_e32 v97, v0
	v_mov_b32_e32 v98, v0
	v_mov_b32_e32 v99, v0
	v_mov_b32_e32 v100, v0
	v_mov_b32_e32 v101, v0
	v_mov_b32_e32 v102, v0
	v_mov_b32_e32 v103, v0
	v_mov_b32_e32 v112, v0
	v_mov_b32_e32 v113, v0
	v_mov_b32_e32 v114, v0
	v_mov_b32_e32 v115, v0
	v_mov_b32_e32 v116, v0
	v_mov_b32_e32 v117, v0
	v_mov_b32_e32 v118, v0
	v_mov_b32_e32 v119, v0
	v_mov_b32_e32 v72, v0
	v_mov_b32_e32 v73, v0
	v_mov_b32_e32 v74, v0
	v_mov_b32_e32 v75, v0
	v_mov_b32_e32 v76, v0
	v_mov_b32_e32 v77, v0
	v_mov_b32_e32 v78, v0
	v_mov_b32_e32 v79, v0
	v_mov_b32_e32 v88, v0
	v_mov_b32_e32 v89, v0
	v_mov_b32_e32 v90, v0
	v_mov_b32_e32 v91, v0
	v_mov_b32_e32 v92, v0
	v_mov_b32_e32 v93, v0
	v_mov_b32_e32 v94, v0
	v_mov_b32_e32 v95, v0
	v_mov_b32_e32 v104, v0
	v_mov_b32_e32 v105, v0
	v_mov_b32_e32 v106, v0
	v_mov_b32_e32 v107, v0
	v_mov_b32_e32 v108, v0
	v_mov_b32_e32 v109, v0
	v_mov_b32_e32 v110, v0
	v_mov_b32_e32 v111, v0
	v_mov_b32_e32 v120, v0
	v_mov_b32_e32 v121, v0
	v_mov_b32_e32 v122, v0
	v_mov_b32_e32 v123, v0
	v_mov_b32_e32 v124, v0
	v_mov_b32_e32 v125, v0
	v_mov_b32_e32 v126, v0
	v_mov_b32_e32 v127, v0
.LBB0_954:
	ds_read_b128 v[144:147], v151
	ds_read_b128 v[156:159], v151 offset:1024
	ds_read_b128 v[160:163], v151 offset:2048
	ds_read_b128 v[164:167], v151 offset:3072
	ds_read_b128 v[168:171], v152
	ds_read_b128 v[172:175], v152 offset:1024
	ds_read_b128 v[176:179], v152 offset:2048
	ds_read_b128 v[180:183], v152 offset:3072
	s_add_u32 s36, s34, 0x3fc000
	s_addc_u32 s37, s35, 0
	s_cmp_eq_u32 s55, 60
	s_cselect_b32 s39, s25, s37
	s_cselect_b32 s38, s31, s36
	s_cselect_b32 s37, s23, s54
	s_cselect_b32 s36, s52, s53
	v_lshl_add_u64 v[216:217], s[34:35], 0, v[136:137]
	s_add_i32 m0, s33, 0xc000
	ds_read_b128 v[184:187], v153
	ds_read_b128 v[188:191], v153 offset:1024
	ds_read_b128 v[192:195], v153 offset:2048
	ds_read_b128 v[196:199], v153 offset:3072
	ds_read_b128 v[200:203], v153 offset:4096
	ds_read_b128 v[204:207], v153 offset:5120
	ds_read_b128 v[208:211], v153 offset:6144
	ds_read_b128 v[212:215], v153 offset:7168
	global_load_lds_dwordx4 v[216:217], off
	v_lshl_add_u64 v[216:217], s[34:35], 0, v[138:139]
	s_add_i32 m0, s33, 0xe000
	s_nop 0
	global_load_lds_dwordx4 v[216:217], off
	s_waitcnt vmcnt(8)
	s_waitcnt lgkmcnt(0)
	s_barrier
	s_setprio 1
	s_waitcnt lgkmcnt(0)
	v_mfma_f32_16x16x32_bf16 v[124:127], v[144:147], v[184:187], v[124:127]
	v_mfma_f32_16x16x32_bf16 v[120:123], v[160:163], v[184:187], v[120:123]
	v_mfma_f32_16x16x32_bf16 v[108:111], v[144:147], v[192:195], v[108:111]
	v_mfma_f32_16x16x32_bf16 v[104:107], v[160:163], v[192:195], v[104:107]
	v_mfma_f32_16x16x32_bf16 v[92:95], v[144:147], v[200:203], v[92:95]
	v_mfma_f32_16x16x32_bf16 v[88:91], v[160:163], v[200:203], v[88:91]
	v_mfma_f32_16x16x32_bf16 v[76:79], v[144:147], v[208:211], v[76:79]
	v_mfma_f32_16x16x32_bf16 v[72:75], v[160:163], v[208:211], v[72:75]
	v_mfma_f32_16x16x32_bf16 v[124:127], v[156:159], v[188:191], v[124:127]
	v_mfma_f32_16x16x32_bf16 v[120:123], v[164:167], v[188:191], v[120:123]
	v_mfma_f32_16x16x32_bf16 v[108:111], v[156:159], v[196:199], v[108:111]
	v_mfma_f32_16x16x32_bf16 v[104:107], v[164:167], v[196:199], v[104:107]
	v_mfma_f32_16x16x32_bf16 v[92:95], v[156:159], v[204:207], v[92:95]
	v_mfma_f32_16x16x32_bf16 v[88:91], v[164:167], v[204:207], v[88:91]
	v_mfma_f32_16x16x32_bf16 v[76:79], v[156:159], v[212:215], v[76:79]
	v_mfma_f32_16x16x32_bf16 v[72:75], v[164:167], v[212:215], v[72:75]
	s_setprio 0
	s_setprio 1
	v_mfma_f32_16x16x32_bf16 v[116:119], v[168:171], v[184:187], v[116:119]
	v_mfma_f32_16x16x32_bf16 v[112:115], v[176:179], v[184:187], v[112:115]
	v_mfma_f32_16x16x32_bf16 v[100:103], v[168:171], v[192:195], v[100:103]
	v_mfma_f32_16x16x32_bf16 v[96:99], v[176:179], v[192:195], v[96:99]
	v_mfma_f32_16x16x32_bf16 v[84:87], v[168:171], v[200:203], v[84:87]
	v_mfma_f32_16x16x32_bf16 v[80:83], v[176:179], v[200:203], v[80:83]
	v_mfma_f32_16x16x32_bf16 v[68:71], v[168:171], v[208:211], v[68:71]
	v_mfma_f32_16x16x32_bf16 v[64:67], v[176:179], v[208:211], v[64:67]
	v_mfma_f32_16x16x32_bf16 v[116:119], v[172:175], v[188:191], v[116:119]
	v_mfma_f32_16x16x32_bf16 v[112:115], v[180:183], v[188:191], v[112:115]
	v_mfma_f32_16x16x32_bf16 v[100:103], v[172:175], v[196:199], v[100:103]
	v_mfma_f32_16x16x32_bf16 v[96:99], v[180:183], v[196:199], v[96:99]
	v_mfma_f32_16x16x32_bf16 v[84:87], v[172:175], v[204:207], v[84:87]
	v_mfma_f32_16x16x32_bf16 v[80:83], v[180:183], v[204:207], v[80:83]
	v_mfma_f32_16x16x32_bf16 v[68:71], v[172:175], v[212:215], v[68:71]
	v_mfma_f32_16x16x32_bf16 v[64:67], v[180:183], v[212:215], v[64:67]
	s_setprio 0
	s_barrier
	s_add_i32 s56, s49, s3
	v_lshl_add_u64 v[216:217], s[36:37], 0, v[130:131]
	s_mov_b32 m0, s56
	ds_read_b128 v[184:187], v153 offset:16384
	ds_read_b128 v[188:191], v153 offset:17408
	ds_read_b128 v[192:195], v153 offset:18432
	ds_read_b128 v[196:199], v153 offset:19456
	ds_read_b128 v[200:203], v153 offset:20480
	ds_read_b128 v[204:207], v153 offset:21504
	ds_read_b128 v[208:211], v153 offset:22528
	ds_read_b128 v[212:215], v153 offset:23552
	global_load_lds_dwordx4 v[216:217], off
	s_add_i32 m0, s56, 0x2000
	s_add_u32 s56, s36, 0x100000
	v_lshl_add_u64 v[218:219], s[36:37], 0, v[134:135]
	s_addc_u32 s57, s37, 0
	s_add_i32 s58, s50, s3
	global_load_lds_dwordx4 v[218:219], off
	v_lshl_add_u64 v[222:223], s[56:57], 0, v[130:131]
	s_mov_b32 m0, s58
	v_lshl_add_u64 v[224:225], s[38:39], 0, v[132:133]
	global_load_lds_dwordx4 v[222:223], off
	v_lshl_add_u64 v[222:223], s[56:57], 0, v[134:135]
	s_add_i32 m0, s58, 0x2000
	s_nop 0
	global_load_lds_dwordx4 v[222:223], off
	v_lshl_add_u64 v[222:223], s[38:39], 0, v[128:129]
	s_mov_b32 m0, s33
	s_nop 0
	global_load_lds_dwordx4 v[222:223], off
	s_mov_b32 m0, s40
	s_nop 0
	global_load_lds_dwordx4 v[224:225], off
	s_waitcnt vmcnt(8)
	s_waitcnt lgkmcnt(0)
	s_barrier
	s_setprio 1
	s_waitcnt lgkmcnt(0)
	v_mfma_f32_16x16x32_bf16 v[60:63], v[144:147], v[184:187], v[60:63]
	v_mfma_f32_16x16x32_bf16 v[56:59], v[160:163], v[184:187], v[56:59]
	v_mfma_f32_16x16x32_bf16 v[44:47], v[144:147], v[192:195], v[44:47]
	v_mfma_f32_16x16x32_bf16 v[40:43], v[160:163], v[192:195], v[40:43]
	v_mfma_f32_16x16x32_bf16 v[28:31], v[144:147], v[200:203], v[28:31]
	v_mfma_f32_16x16x32_bf16 v[24:27], v[160:163], v[200:203], v[24:27]
	v_mfma_f32_16x16x32_bf16 v[12:15], v[144:147], v[208:211], v[12:15]
	v_mfma_f32_16x16x32_bf16 v[8:11], v[160:163], v[208:211], v[8:11]
	v_mfma_f32_16x16x32_bf16 v[60:63], v[156:159], v[188:191], v[60:63]
	v_mfma_f32_16x16x32_bf16 v[56:59], v[164:167], v[188:191], v[56:59]
	v_mfma_f32_16x16x32_bf16 v[44:47], v[156:159], v[196:199], v[44:47]
	v_mfma_f32_16x16x32_bf16 v[40:43], v[164:167], v[196:199], v[40:43]
	v_mfma_f32_16x16x32_bf16 v[28:31], v[156:159], v[204:207], v[28:31]
	v_mfma_f32_16x16x32_bf16 v[24:27], v[164:167], v[204:207], v[24:27]
	v_mfma_f32_16x16x32_bf16 v[12:15], v[156:159], v[212:215], v[12:15]
	v_mfma_f32_16x16x32_bf16 v[8:11], v[164:167], v[212:215], v[8:11]
	s_setprio 0
	s_setprio 1
	v_mfma_f32_16x16x32_bf16 v[52:55], v[168:171], v[184:187], v[52:55]
	v_mfma_f32_16x16x32_bf16 v[48:51], v[176:179], v[184:187], v[48:51]
	v_mfma_f32_16x16x32_bf16 v[36:39], v[168:171], v[192:195], v[36:39]
	v_mfma_f32_16x16x32_bf16 v[32:35], v[176:179], v[192:195], v[32:35]
	v_mfma_f32_16x16x32_bf16 v[20:23], v[168:171], v[200:203], v[20:23]
	v_mfma_f32_16x16x32_bf16 v[16:19], v[176:179], v[200:203], v[16:19]
	v_mfma_f32_16x16x32_bf16 v[4:7], v[168:171], v[208:211], v[4:7]
	v_mfma_f32_16x16x32_bf16 v[0:3], v[176:179], v[208:211], v[0:3]
	v_mfma_f32_16x16x32_bf16 v[52:55], v[172:175], v[188:191], v[52:55]
	v_mfma_f32_16x16x32_bf16 v[48:51], v[180:183], v[188:191], v[48:51]
	v_mfma_f32_16x16x32_bf16 v[36:39], v[172:175], v[196:199], v[36:39]
	v_mfma_f32_16x16x32_bf16 v[32:35], v[180:183], v[196:199], v[32:35]
	v_mfma_f32_16x16x32_bf16 v[20:23], v[172:175], v[204:207], v[20:23]
	v_mfma_f32_16x16x32_bf16 v[16:19], v[180:183], v[204:207], v[16:19]
	v_mfma_f32_16x16x32_bf16 v[4:7], v[172:175], v[212:215], v[4:7]
	v_mfma_f32_16x16x32_bf16 v[0:3], v[180:183], v[212:215], v[0:3]
	s_setprio 0
	s_barrier
	s_add_i32 s56, 0, 0x18000
	v_add_u32_e32 v155, s56, v149
	s_add_i32 s57, 0, 0x1c000
	ds_read_b128 v[144:147], v155
	ds_read_b128 v[156:159], v155 offset:1024
	ds_read_b128 v[160:163], v155 offset:2048
	ds_read_b128 v[164:167], v155 offset:3072
	v_add_u32_e32 v155, s57, v149
	ds_read_b128 v[168:171], v155
	ds_read_b128 v[172:175], v155 offset:1024
	ds_read_b128 v[176:179], v155 offset:2048
	ds_read_b128 v[180:183], v155 offset:3072
	s_add_u32 s38, s38, 0x4000
	s_addc_u32 s39, s39, 0
	s_mov_b32 m0, s41
	v_lshl_add_u64 v[226:227], s[38:39], 0, v[128:129]
	ds_read_b128 v[184:187], v153 offset:32768
	ds_read_b128 v[188:191], v153 offset:33792
	ds_read_b128 v[192:195], v153 offset:34816
	ds_read_b128 v[196:199], v153 offset:35840
	ds_read_b128 v[200:203], v153 offset:36864
	ds_read_b128 v[204:207], v153 offset:37888
	ds_read_b128 v[208:211], v153 offset:38912
	ds_read_b128 v[212:215], v153 offset:39936
	global_load_lds_dwordx4 v[226:227], off
	v_lshl_add_u64 v[226:227], s[38:39], 0, v[132:133]
	s_mov_b32 m0, s42
	s_nop 0
	global_load_lds_dwordx4 v[226:227], off
	s_waitcnt vmcnt(8)
	s_waitcnt lgkmcnt(0)
	s_barrier
	s_setprio 1
	s_waitcnt lgkmcnt(0)
	v_mfma_f32_16x16x32_bf16 v[124:127], v[144:147], v[184:187], v[124:127]
	v_mfma_f32_16x16x32_bf16 v[120:123], v[160:163], v[184:187], v[120:123]
	v_mfma_f32_16x16x32_bf16 v[108:111], v[144:147], v[192:195], v[108:111]
	v_mfma_f32_16x16x32_bf16 v[104:107], v[160:163], v[192:195], v[104:107]
	v_mfma_f32_16x16x32_bf16 v[92:95], v[144:147], v[200:203], v[92:95]
	v_mfma_f32_16x16x32_bf16 v[88:91], v[160:163], v[200:203], v[88:91]
	v_mfma_f32_16x16x32_bf16 v[76:79], v[144:147], v[208:211], v[76:79]
	v_mfma_f32_16x16x32_bf16 v[72:75], v[160:163], v[208:211], v[72:75]
	v_mfma_f32_16x16x32_bf16 v[124:127], v[156:159], v[188:191], v[124:127]
	v_mfma_f32_16x16x32_bf16 v[120:123], v[164:167], v[188:191], v[120:123]
	v_mfma_f32_16x16x32_bf16 v[108:111], v[156:159], v[196:199], v[108:111]
	v_mfma_f32_16x16x32_bf16 v[104:107], v[164:167], v[196:199], v[104:107]
	v_mfma_f32_16x16x32_bf16 v[92:95], v[156:159], v[204:207], v[92:95]
	v_mfma_f32_16x16x32_bf16 v[88:91], v[164:167], v[204:207], v[88:91]
	v_mfma_f32_16x16x32_bf16 v[76:79], v[156:159], v[212:215], v[76:79]
	v_mfma_f32_16x16x32_bf16 v[72:75], v[164:167], v[212:215], v[72:75]
	s_setprio 0
	s_setprio 1
	v_mfma_f32_16x16x32_bf16 v[116:119], v[168:171], v[184:187], v[116:119]
	v_mfma_f32_16x16x32_bf16 v[112:115], v[176:179], v[184:187], v[112:115]
	v_mfma_f32_16x16x32_bf16 v[100:103], v[168:171], v[192:195], v[100:103]
	v_mfma_f32_16x16x32_bf16 v[96:99], v[176:179], v[192:195], v[96:99]
	v_mfma_f32_16x16x32_bf16 v[84:87], v[168:171], v[200:203], v[84:87]
	v_mfma_f32_16x16x32_bf16 v[80:83], v[176:179], v[200:203], v[80:83]
	v_mfma_f32_16x16x32_bf16 v[68:71], v[168:171], v[208:211], v[68:71]
	v_mfma_f32_16x16x32_bf16 v[64:67], v[176:179], v[208:211], v[64:67]
	v_mfma_f32_16x16x32_bf16 v[116:119], v[172:175], v[188:191], v[116:119]
	v_mfma_f32_16x16x32_bf16 v[112:115], v[180:183], v[188:191], v[112:115]
	v_mfma_f32_16x16x32_bf16 v[100:103], v[172:175], v[196:199], v[100:103]
	v_mfma_f32_16x16x32_bf16 v[96:99], v[180:183], v[196:199], v[96:99]
	v_mfma_f32_16x16x32_bf16 v[84:87], v[172:175], v[204:207], v[84:87]
	v_mfma_f32_16x16x32_bf16 v[80:83], v[180:183], v[204:207], v[80:83]
	v_mfma_f32_16x16x32_bf16 v[68:71], v[172:175], v[212:215], v[68:71]
	v_mfma_f32_16x16x32_bf16 v[64:67], v[180:183], v[212:215], v[64:67]
	s_setprio 0
	s_barrier
	s_add_i32 s38, s56, s3
	v_lshl_add_u64 v[216:217], v[216:217], 0, s[18:19]
	s_mov_b32 m0, s38
	ds_read_b128 v[184:187], v153 offset:49152
	ds_read_b128 v[188:191], v153 offset:50176
	ds_read_b128 v[192:195], v153 offset:51200
	ds_read_b128 v[196:199], v153 offset:52224
	ds_read_b128 v[200:203], v153 offset:53248
	ds_read_b128 v[204:207], v153 offset:54272
	ds_read_b128 v[208:211], v153 offset:55296
	ds_read_b128 v[212:215], v153 offset:56320
	global_load_lds_dwordx4 v[216:217], off
	s_add_i32 m0, s38, 0x2000
	s_add_u32 s36, s36, 0x100080
	v_lshl_add_u64 v[216:217], v[218:219], 0, s[18:19]
	s_addc_u32 s37, s37, 0
	s_add_i32 s38, s57, s3
	global_load_lds_dwordx4 v[216:217], off
	v_lshl_add_u64 v[216:217], s[36:37], 0, v[130:131]
	s_mov_b32 m0, s38
	s_nop 0
	global_load_lds_dwordx4 v[216:217], off
	v_lshl_add_u64 v[216:217], s[36:37], 0, v[134:135]
	s_add_i32 m0, s38, 0x2000
	s_nop 0
	global_load_lds_dwordx4 v[216:217], off
	v_lshl_add_u64 v[216:217], v[222:223], 0, s[98:99]
	s_mov_b32 m0, s46
	s_nop 0
	global_load_lds_dwordx4 v[216:217], off
	v_lshl_add_u64 v[216:217], v[224:225], 0, s[98:99]
	s_mov_b32 m0, s47
	s_nop 0
	global_load_lds_dwordx4 v[216:217], off
	s_waitcnt vmcnt(8)
	s_waitcnt lgkmcnt(0)
	s_barrier
	s_setprio 1
	s_waitcnt lgkmcnt(0)
	v_mfma_f32_16x16x32_bf16 v[60:63], v[144:147], v[184:187], v[60:63]
	v_mfma_f32_16x16x32_bf16 v[56:59], v[160:163], v[184:187], v[56:59]
	v_mfma_f32_16x16x32_bf16 v[44:47], v[144:147], v[192:195], v[44:47]
	v_mfma_f32_16x16x32_bf16 v[40:43], v[160:163], v[192:195], v[40:43]
	v_mfma_f32_16x16x32_bf16 v[28:31], v[144:147], v[200:203], v[28:31]
	v_mfma_f32_16x16x32_bf16 v[24:27], v[160:163], v[200:203], v[24:27]
	v_mfma_f32_16x16x32_bf16 v[12:15], v[144:147], v[208:211], v[12:15]
	v_mfma_f32_16x16x32_bf16 v[8:11], v[160:163], v[208:211], v[8:11]
	v_mfma_f32_16x16x32_bf16 v[60:63], v[156:159], v[188:191], v[60:63]
	v_mfma_f32_16x16x32_bf16 v[56:59], v[164:167], v[188:191], v[56:59]
	v_mfma_f32_16x16x32_bf16 v[44:47], v[156:159], v[196:199], v[44:47]
	v_mfma_f32_16x16x32_bf16 v[40:43], v[164:167], v[196:199], v[40:43]
	v_mfma_f32_16x16x32_bf16 v[28:31], v[156:159], v[204:207], v[28:31]
	v_mfma_f32_16x16x32_bf16 v[24:27], v[164:167], v[204:207], v[24:27]
	v_mfma_f32_16x16x32_bf16 v[12:15], v[156:159], v[212:215], v[12:15]
	v_mfma_f32_16x16x32_bf16 v[8:11], v[164:167], v[212:215], v[8:11]
	s_setprio 0
	s_setprio 1
	v_mfma_f32_16x16x32_bf16 v[52:55], v[168:171], v[184:187], v[52:55]
	v_mfma_f32_16x16x32_bf16 v[48:51], v[176:179], v[184:187], v[48:51]
	v_mfma_f32_16x16x32_bf16 v[36:39], v[168:171], v[192:195], v[36:39]
	v_mfma_f32_16x16x32_bf16 v[32:35], v[176:179], v[192:195], v[32:35]
	v_mfma_f32_16x16x32_bf16 v[20:23], v[168:171], v[200:203], v[20:23]
	v_mfma_f32_16x16x32_bf16 v[16:19], v[176:179], v[200:203], v[16:19]
	v_mfma_f32_16x16x32_bf16 v[4:7], v[168:171], v[208:211], v[4:7]
	v_mfma_f32_16x16x32_bf16 v[0:3], v[176:179], v[208:211], v[0:3]
	v_mfma_f32_16x16x32_bf16 v[52:55], v[172:175], v[188:191], v[52:55]
	v_mfma_f32_16x16x32_bf16 v[48:51], v[180:183], v[188:191], v[48:51]
	v_mfma_f32_16x16x32_bf16 v[36:39], v[172:175], v[196:199], v[36:39]
	v_mfma_f32_16x16x32_bf16 v[32:35], v[180:183], v[196:199], v[32:35]
	v_mfma_f32_16x16x32_bf16 v[20:23], v[172:175], v[204:207], v[20:23]
	v_mfma_f32_16x16x32_bf16 v[16:19], v[180:183], v[204:207], v[16:19]
	v_mfma_f32_16x16x32_bf16 v[4:7], v[172:175], v[212:215], v[4:7]
	v_mfma_f32_16x16x32_bf16 v[0:3], v[180:183], v[212:215], v[0:3]
	s_setprio 0
	s_barrier
	s_add_i32 s55, s55, 2
	s_add_u32 s34, s34, 0x800000
	s_addc_u32 s35, s35, 0
	s_add_u32 s53, s53, 0x100
	s_addc_u32 s54, s54, 0
	s_cmp_gt_u32 s55, 61
	s_cbranch_scc0 .LBB0_954
	s_and_b64 vcc, exec, s[20:21]
	s_cbranch_vccz .LBB0_957
	s_barrier

	.amdhsa_kernel _Z10fwd_kernel4Args
		.amdhsa_group_segment_fixed_size 0
		.amdhsa_private_segment_fixed_size 0
		.amdhsa_kernarg_size 432
		.amdhsa_user_sgpr_count 2
		.amdhsa_user_sgpr_dispatch_ptr 0
		.amdhsa_user_sgpr_queue_ptr 0
		.amdhsa_user_sgpr_kernarg_segment_ptr 1
		.amdhsa_user_sgpr_dispatch_id 0
		.amdhsa_user_sgpr_kernarg_preload_length 0
		.amdhsa_user_sgpr_kernarg_preload_offset 0
		.amdhsa_user_sgpr_private_segment_size 0
		.amdhsa_uses_dynamic_stack 0
		.amdhsa_enable_private_segment 0
		.amdhsa_system_sgpr_workgroup_id_x 1
		.amdhsa_system_sgpr_workgroup_id_y 0
		.amdhsa_system_sgpr_workgroup_id_z 0
		.amdhsa_system_sgpr_workgroup_info 0
		.amdhsa_system_vgpr_workitem_id 2
		.amdhsa_next_free_vgpr 255
		.amdhsa_next_free_sgpr 100
		.amdhsa_accum_offset 256
		.amdhsa_reserve_vcc 1
		.amdhsa_float_round_mode_32 0
		.amdhsa_float_round_mode_16_64 0
		.amdhsa_float_denorm_mode_32 3
		.amdhsa_float_denorm_mode_16_64 3
		.amdhsa_dx10_clamp 1
		.amdhsa_ieee_mode 1
		.amdhsa_fp16_overflow 0
		.amdhsa_tg_split 0
		.amdhsa_exception_fp_ieee_invalid_op 0
		.amdhsa_exception_fp_denorm_src 0
		.amdhsa_exception_fp_ieee_div_zero 0
		.amdhsa_exception_fp_ieee_overflow 0
		.amdhsa_exception_fp_ieee_underflow 0
		.amdhsa_exception_fp_ieee_inexact 0
		.amdhsa_exception_int_div_zero 0
	.end_amdhsa_kernel

amdhsa.kernels:
  - .agpr_count:     0
    .args:
      - .offset:         0
        .size:           176
        .value_kind:     by_value
      - .offset:         176
        .size:           4
        .value_kind:     hidden_block_count_x
      - .offset:         180
        .size:           4
        .value_kind:     hidden_block_count_y
      - .offset:         184
        .size:           4
        .value_kind:     hidden_block_count_z
      - .offset:         188
        .size:           2
        .value_kind:     hidden_group_size_x
      - .offset:         190
        .size:           2
        .value_kind:     hidden_group_size_y
      - .offset:         192
        .size:           2
        .value_kind:     hidden_group_size_z
      - .offset:         194
        .size:           2
        .value_kind:     hidden_remainder_x
      - .offset:         196
        .size:           2
        .value_kind:     hidden_remainder_y
      - .offset:         198
        .size:           2
        .value_kind:     hidden_remainder_z
      - .offset:         216
        .size:           8
        .value_kind:     hidden_global_offset_x
      - .offset:         224
        .size:           8
        .value_kind:     hidden_global_offset_y
      - .offset:         232
        .size:           8
        .value_kind:     hidden_global_offset_z
      - .offset:         240
        .size:           2
        .value_kind:     hidden_grid_dims
      - .offset:         264
        .size:           8
        .value_kind:     hidden_multigrid_sync_arg
      - .offset:         296
        .size:           4
        .value_kind:     hidden_dynamic_lds_size
    .group_segment_fixed_size: 0
    .kernarg_segment_align: 8
    .kernarg_segment_size: 432
    .language:       OpenCL C
    .language_version:
      - 2
      - 0
    .max_flat_workgroup_size: 512
    .name:           _Z10fwd_kernel4Args
    .private_segment_fixed_size: 0
    .sgpr_count:     106
    .sgpr_spill_count: 53
    .symbol:         _Z10fwd_kernel4Args.kd
    .uniform_work_group_size: 1
    .uses_dynamic_stack: false
    .vgpr_count:     255
    .vgpr_spill_count: 0
    .wavefront_size: 64
